# MIX work queue: next-item atomic returns into v166 and is waited at item end instead of item start; stacked on stack13
# speedup vs baseline: 1.0385x; 1.0385x over previous
; __global__ void __launch_bounds__(NTHR, 2) mk_fwd(Args a) {
;     ...
;                 for (int it = 0;; ++it) {
;                     int idx, bsel; unsigned nxt = 0u;
;                     if (useq) { idx = (int)qw[it & 1]; if (idx >= 160) break; bsel = xg; if (tid == 0) nxt = __hip_atomic_fetch_add(qcnt, 1u, __ATOMIC_RELAXED, __HIP_MEMORY_SCOPE_AGENT); }
;                     else { if (sidx >= BATCH * 160) break; bsel = sidx / 160; idx = sidx % 160; sidx += G; }
;                     const int cls = idx >> 4, e = idx & 15;
.LBB0_300:
	s_and_b32 s14, s88, 1
	s_lshl_b32 s14, s14, 2
	s_add_i32 s14, s14, 0
	s_add_i32 s14, s14, 0x22040
	v_mov_b32_e32 v0, s14
	ds_read_b32 v0, v0
	s_movk_i32 s14, 0xa0
	s_waitcnt lgkmcnt(0)
	v_cmp_gt_i32_e32 vcc, s14, v0
	v_readfirstlane_b32 s16, v0
	s_cbranch_vccz .LBB0_306
	v_mov_b32_e32 v166, 0
	s_mov_b64 s[36:37], exec
	v_readlane_b32 s14, v253, 0
	v_readlane_b32 s15, v253, 1
	s_and_b64 s[14:15], s[36:37], s[14:15]
	s_mov_b64 exec, s[14:15]
	s_cbranch_execz .LBB0_305
	s_mov_b64 s[40:41], exec
	v_mbcnt_lo_u32_b32 v0, s40, 0
	v_mbcnt_hi_u32_b32 v0, s41, v0
	v_cmp_eq_u32_e32 vcc, 0, v0
	s_and_saveexec_b64 s[38:39], vcc
	s_cbranch_execz .LBB0_304
	s_bcnt1_i32_b64 s14, s[40:41]
	v_mov_b32_e32 v1, s14
	v_readlane_b32 s14, v255, 24
	v_readlane_b32 s15, v255, 25
	s_nop 4
	global_atomic_add v166, v129, v1, s[14:15] sc0
.LBB0_304:
	s_or_b64 exec, exec, s[38:39]
.LBB0_305:
	s_or_b64 exec, exec, s[36:37]
	s_mov_b64 s[38:39], -1

; __global__ void __launch_bounds__(NTHR, 2) mk_fwd(Args a) {
;     ...
;                     if (useq && tid == 0) qw[(it + 1) & 1] = nxt;
;                     __syncthreads();
.LBB0_407:
	s_mov_b64 s[36:37], exec
	v_readlane_b32 s14, v253, 58
	v_readlane_b32 s15, v253, 59
	s_and_b64 s[14:15], s[36:37], s[14:15]
	s_mov_b64 exec, s[14:15]
	s_cbranch_execz .LBB0_294
	s_andn2_b32 s14, 1, s88
	s_lshl_b32 s14, s14, 2
	s_add_i32 s14, s14, 0
	s_add_i32 s14, s14, 0x22040
	v_mov_b32_e32 v0, s14
	s_waitcnt vmcnt(0)
	ds_write_b32 v0, v166
	s_branch .LBB0_294
